# BM selected-attention near-block path: relative-bias LUT reads issued in two batches of eight with one wait each instead of eight waits of two
# baseline (speedup 1.0000x reference)
.Lbm2_Ag0_near:
	s_lshl_b32 s13, s54, 6
	s_sub_i32 s13, s97, s13
	v_and_b32_e32 v245, 15, v181
	v_lshrrev_b32_e32 v246, 4, v181
	v_lshrrev_b32_e32 v245, 2, v245
	v_lshlrev_b32_e32 v246, 2, v246
	v_cndmask_b32_e32 v200, v77, v190, vcc
	v_sub_u32_e32 v245, v245, v246
	v_add_u32_e32 v198, s13, v245
	v_min_u32_e32 v82, 0x7f, v198
	v_lshl_add_u32 v82, v82, 2, v80
	ds_read_b32 v82, v82
	v_subrev_u32_e32 v245, 1, v198
	v_min_u32_e32 v83, 0x7f, v245
	v_lshl_add_u32 v83, v83, 2, v80
	ds_read_b32 v83, v83
	v_subrev_u32_e32 v245, 2, v198
	v_min_u32_e32 v172, 0x7f, v245
	v_lshl_add_u32 v172, v172, 2, v80
	ds_read_b32 v172, v172
	v_subrev_u32_e32 v245, 3, v198
	v_min_u32_e32 v173, 0x7f, v245
	v_lshl_add_u32 v173, v173, 2, v80
	ds_read_b32 v173, v173
	v_subrev_u32_e32 v245, 16, v198
	v_min_u32_e32 v202, 0x7f, v245
	v_lshl_add_u32 v202, v202, 2, v80
	ds_read_b32 v202, v202
	v_subrev_u32_e32 v245, 17, v198
	v_min_u32_e32 v203, 0x7f, v245
	v_lshl_add_u32 v203, v203, 2, v80
	ds_read_b32 v203, v203
	v_subrev_u32_e32 v245, 18, v198
	v_min_u32_e32 v228, 0x7f, v245
	v_lshl_add_u32 v228, v228, 2, v80
	ds_read_b32 v228, v228
	v_subrev_u32_e32 v245, 19, v198
	v_min_u32_e32 v229, 0x7f, v245
	v_lshl_add_u32 v229, v229, 2, v80
	ds_read_b32 v229, v229
	s_waitcnt lgkmcnt(0)
	v_fmamk_f32 v82, v82, 0x3fb8aa3b, v200
	v_cmp_le_i32_e32 vcc, 0, v198
	v_fmamk_f32 v84, v84, 0x3e38aa3b, v82
	s_nop 0
	v_cndmask_b32_e32 v84, v77, v84, vcc
	v_fmamk_f32 v83, v83, 0x3fb8aa3b, v200
	v_cmp_le_i32_e32 vcc, 1, v198
	v_fmamk_f32 v85, v85, 0x3e38aa3b, v83
	s_nop 0
	v_cndmask_b32_e32 v85, v77, v85, vcc
	v_fmamk_f32 v172, v172, 0x3fb8aa3b, v200
	v_cmp_le_i32_e32 vcc, 2, v198
	v_fmamk_f32 v86, v86, 0x3e38aa3b, v172
	s_nop 0
	v_cndmask_b32_e32 v86, v77, v86, vcc
	v_fmamk_f32 v173, v173, 0x3fb8aa3b, v200
	v_cmp_le_i32_e32 vcc, 3, v198
	v_fmamk_f32 v87, v87, 0x3e38aa3b, v173
	s_nop 0
	v_cndmask_b32_e32 v87, v77, v87, vcc
	v_fmamk_f32 v202, v202, 0x3fb8aa3b, v200
	v_cmp_le_i32_e32 vcc, 16, v198
	v_fmamk_f32 v88, v88, 0x3e38aa3b, v202
	s_nop 0
	v_cndmask_b32_e32 v88, v77, v88, vcc
	v_fmamk_f32 v203, v203, 0x3fb8aa3b, v200
	v_cmp_le_i32_e32 vcc, 17, v198
	v_fmamk_f32 v89, v89, 0x3e38aa3b, v203
	s_nop 0
	v_cndmask_b32_e32 v89, v77, v89, vcc
	v_fmamk_f32 v228, v228, 0x3fb8aa3b, v200
	v_cmp_le_i32_e32 vcc, 18, v198
	v_fmamk_f32 v90, v90, 0x3e38aa3b, v228
	s_nop 0
	v_cndmask_b32_e32 v90, v77, v90, vcc
	v_fmamk_f32 v229, v229, 0x3fb8aa3b, v200
	v_cmp_le_i32_e32 vcc, 19, v198
	v_fmamk_f32 v91, v91, 0x3e38aa3b, v229
	s_nop 0
	v_cndmask_b32_e32 v91, v77, v91, vcc
	v_subrev_u32_e32 v245, 32, v198
	v_min_u32_e32 v82, 0x7f, v245
	v_lshl_add_u32 v82, v82, 2, v80
	ds_read_b32 v82, v82
	v_subrev_u32_e32 v245, 33, v198
	v_min_u32_e32 v83, 0x7f, v245
	v_lshl_add_u32 v83, v83, 2, v80
	ds_read_b32 v83, v83
	v_subrev_u32_e32 v245, 34, v198
	v_min_u32_e32 v172, 0x7f, v245
	v_lshl_add_u32 v172, v172, 2, v80
	ds_read_b32 v172, v172
	v_subrev_u32_e32 v245, 35, v198
	v_min_u32_e32 v173, 0x7f, v245
	v_lshl_add_u32 v173, v173, 2, v80
	ds_read_b32 v173, v173
	v_subrev_u32_e32 v245, 48, v198
	v_min_u32_e32 v202, 0x7f, v245
	v_lshl_add_u32 v202, v202, 2, v80
	ds_read_b32 v202, v202
	v_subrev_u32_e32 v245, 49, v198
	v_min_u32_e32 v203, 0x7f, v245
	v_lshl_add_u32 v203, v203, 2, v80
	ds_read_b32 v203, v203
	v_subrev_u32_e32 v245, 50, v198
	v_min_u32_e32 v228, 0x7f, v245
	v_lshl_add_u32 v228, v228, 2, v80
	ds_read_b32 v228, v228
	v_subrev_u32_e32 v245, 51, v198
	v_min_u32_e32 v229, 0x7f, v245
	v_lshl_add_u32 v229, v229, 2, v80
	ds_read_b32 v229, v229
	s_waitcnt lgkmcnt(0)
	v_fmamk_f32 v82, v82, 0x3fb8aa3b, v200
	v_cmp_le_i32_e32 vcc, 32, v198
	v_fmamk_f32 v92, v92, 0x3e38aa3b, v82
	s_nop 0
	v_cndmask_b32_e32 v92, v77, v92, vcc
	v_fmamk_f32 v83, v83, 0x3fb8aa3b, v200
	v_cmp_le_i32_e32 vcc, 33, v198
	v_fmamk_f32 v93, v93, 0x3e38aa3b, v83
	s_nop 0
	v_cndmask_b32_e32 v93, v77, v93, vcc
	v_fmamk_f32 v172, v172, 0x3fb8aa3b, v200
	v_cmp_le_i32_e32 vcc, 34, v198
	v_fmamk_f32 v94, v94, 0x3e38aa3b, v172
	s_nop 0
	v_cndmask_b32_e32 v94, v77, v94, vcc
	v_fmamk_f32 v173, v173, 0x3fb8aa3b, v200
	v_cmp_le_i32_e32 vcc, 35, v198
	v_fmamk_f32 v95, v95, 0x3e38aa3b, v173
	s_nop 0
	v_cndmask_b32_e32 v95, v77, v95, vcc
	v_fmamk_f32 v202, v202, 0x3fb8aa3b, v200
	v_cmp_le_i32_e32 vcc, 48, v198
	v_fmamk_f32 v96, v96, 0x3e38aa3b, v202
	s_nop 0
	v_cndmask_b32_e32 v96, v77, v96, vcc
	v_fmamk_f32 v203, v203, 0x3fb8aa3b, v200
	v_cmp_le_i32_e32 vcc, 49, v198
	v_fmamk_f32 v97, v97, 0x3e38aa3b, v203
	s_nop 0
	v_cndmask_b32_e32 v97, v77, v97, vcc
	v_fmamk_f32 v228, v228, 0x3fb8aa3b, v200
	v_cmp_le_i32_e32 vcc, 50, v198
	v_fmamk_f32 v98, v98, 0x3e38aa3b, v228
	s_nop 0
	v_cndmask_b32_e32 v98, v77, v98, vcc
	v_fmamk_f32 v229, v229, 0x3fb8aa3b, v200
	v_cmp_le_i32_e32 vcc, 51, v198
	v_fmamk_f32 v99, v99, 0x3e38aa3b, v229
	s_nop 0
	v_cndmask_b32_e32 v99, v77, v99, vcc
	s_branch .Lbm2_Ag0_max

.Lbm2_Ag1_near:
	s_lshl_b32 s13, s54, 6
	s_sub_i32 s13, s97, s13
	s_add_i32 s13, s13, 4
	v_and_b32_e32 v245, 15, v181
	v_lshrrev_b32_e32 v246, 4, v181
	v_lshrrev_b32_e32 v245, 2, v245
	v_lshlrev_b32_e32 v246, 2, v246
	v_cndmask_b32_e32 v200, v77, v191, vcc
	v_sub_u32_e32 v245, v245, v246
	v_add_u32_e32 v198, s13, v245
	v_min_u32_e32 v82, 0x7f, v198
	v_lshl_add_u32 v82, v82, 2, v80
	ds_read_b32 v82, v82
	v_subrev_u32_e32 v245, 1, v198
	v_min_u32_e32 v83, 0x7f, v245
	v_lshl_add_u32 v83, v83, 2, v80
	ds_read_b32 v83, v83
	v_subrev_u32_e32 v245, 2, v198
	v_min_u32_e32 v172, 0x7f, v245
	v_lshl_add_u32 v172, v172, 2, v80
	ds_read_b32 v172, v172
	v_subrev_u32_e32 v245, 3, v198
	v_min_u32_e32 v173, 0x7f, v245
	v_lshl_add_u32 v173, v173, 2, v80
	ds_read_b32 v173, v173
	v_subrev_u32_e32 v245, 16, v198
	v_min_u32_e32 v202, 0x7f, v245
	v_lshl_add_u32 v202, v202, 2, v80
	ds_read_b32 v202, v202
	v_subrev_u32_e32 v245, 17, v198
	v_min_u32_e32 v203, 0x7f, v245
	v_lshl_add_u32 v203, v203, 2, v80
	ds_read_b32 v203, v203
	v_subrev_u32_e32 v245, 18, v198
	v_min_u32_e32 v228, 0x7f, v245
	v_lshl_add_u32 v228, v228, 2, v80
	ds_read_b32 v228, v228
	v_subrev_u32_e32 v245, 19, v198
	v_min_u32_e32 v229, 0x7f, v245
	v_lshl_add_u32 v229, v229, 2, v80
	ds_read_b32 v229, v229
	s_waitcnt lgkmcnt(0)
	v_fmamk_f32 v82, v82, 0x3fb8aa3b, v200
	v_cmp_le_i32_e32 vcc, 0, v198
	v_fmamk_f32 v84, v84, 0x3e38aa3b, v82
	s_nop 0
	v_cndmask_b32_e32 v84, v77, v84, vcc
	v_fmamk_f32 v83, v83, 0x3fb8aa3b, v200
	v_cmp_le_i32_e32 vcc, 1, v198
	v_fmamk_f32 v85, v85, 0x3e38aa3b, v83
	s_nop 0
	v_cndmask_b32_e32 v85, v77, v85, vcc
	v_fmamk_f32 v172, v172, 0x3fb8aa3b, v200
	v_cmp_le_i32_e32 vcc, 2, v198
	v_fmamk_f32 v86, v86, 0x3e38aa3b, v172
	s_nop 0
	v_cndmask_b32_e32 v86, v77, v86, vcc
	v_fmamk_f32 v173, v173, 0x3fb8aa3b, v200
	v_cmp_le_i32_e32 vcc, 3, v198
	v_fmamk_f32 v87, v87, 0x3e38aa3b, v173
	s_nop 0
	v_cndmask_b32_e32 v87, v77, v87, vcc
	v_fmamk_f32 v202, v202, 0x3fb8aa3b, v200
	v_cmp_le_i32_e32 vcc, 16, v198
	v_fmamk_f32 v88, v88, 0x3e38aa3b, v202
	s_nop 0
	v_cndmask_b32_e32 v88, v77, v88, vcc
	v_fmamk_f32 v203, v203, 0x3fb8aa3b, v200
	v_cmp_le_i32_e32 vcc, 17, v198
	v_fmamk_f32 v89, v89, 0x3e38aa3b, v203
	s_nop 0
	v_cndmask_b32_e32 v89, v77, v89, vcc
	v_fmamk_f32 v228, v228, 0x3fb8aa3b, v200
	v_cmp_le_i32_e32 vcc, 18, v198
	v_fmamk_f32 v90, v90, 0x3e38aa3b, v228
	s_nop 0
	v_cndmask_b32_e32 v90, v77, v90, vcc
	v_fmamk_f32 v229, v229, 0x3fb8aa3b, v200
	v_cmp_le_i32_e32 vcc, 19, v198
	v_fmamk_f32 v91, v91, 0x3e38aa3b, v229
	s_nop 0
	v_cndmask_b32_e32 v91, v77, v91, vcc
	v_subrev_u32_e32 v245, 32, v198
	v_min_u32_e32 v82, 0x7f, v245
	v_lshl_add_u32 v82, v82, 2, v80
	ds_read_b32 v82, v82
	v_subrev_u32_e32 v245, 33, v198
	v_min_u32_e32 v83, 0x7f, v245
	v_lshl_add_u32 v83, v83, 2, v80
	ds_read_b32 v83, v83
	v_subrev_u32_e32 v245, 34, v198
	v_min_u32_e32 v172, 0x7f, v245
	v_lshl_add_u32 v172, v172, 2, v80
	ds_read_b32 v172, v172
	v_subrev_u32_e32 v245, 35, v198
	v_min_u32_e32 v173, 0x7f, v245
	v_lshl_add_u32 v173, v173, 2, v80
	ds_read_b32 v173, v173
	v_subrev_u32_e32 v245, 48, v198
	v_min_u32_e32 v202, 0x7f, v245
	v_lshl_add_u32 v202, v202, 2, v80
	ds_read_b32 v202, v202
	v_subrev_u32_e32 v245, 49, v198
	v_min_u32_e32 v203, 0x7f, v245
	v_lshl_add_u32 v203, v203, 2, v80
	ds_read_b32 v203, v203
	v_subrev_u32_e32 v245, 50, v198
	v_min_u32_e32 v228, 0x7f, v245
	v_lshl_add_u32 v228, v228, 2, v80
	ds_read_b32 v228, v228
	v_subrev_u32_e32 v245, 51, v198
	v_min_u32_e32 v229, 0x7f, v245
	v_lshl_add_u32 v229, v229, 2, v80
	ds_read_b32 v229, v229
	s_waitcnt lgkmcnt(0)
	v_fmamk_f32 v82, v82, 0x3fb8aa3b, v200
	v_cmp_le_i32_e32 vcc, 32, v198
	v_fmamk_f32 v92, v92, 0x3e38aa3b, v82
	s_nop 0
	v_cndmask_b32_e32 v92, v77, v92, vcc
	v_fmamk_f32 v83, v83, 0x3fb8aa3b, v200
	v_cmp_le_i32_e32 vcc, 33, v198
	v_fmamk_f32 v93, v93, 0x3e38aa3b, v83
	s_nop 0
	v_cndmask_b32_e32 v93, v77, v93, vcc
	v_fmamk_f32 v172, v172, 0x3fb8aa3b, v200
	v_cmp_le_i32_e32 vcc, 34, v198
	v_fmamk_f32 v94, v94, 0x3e38aa3b, v172
	s_nop 0
	v_cndmask_b32_e32 v94, v77, v94, vcc
	v_fmamk_f32 v173, v173, 0x3fb8aa3b, v200
	v_cmp_le_i32_e32 vcc, 35, v198
	v_fmamk_f32 v95, v95, 0x3e38aa3b, v173
	s_nop 0
	v_cndmask_b32_e32 v95, v77, v95, vcc
	v_fmamk_f32 v202, v202, 0x3fb8aa3b, v200
	v_cmp_le_i32_e32 vcc, 48, v198
	v_fmamk_f32 v96, v96, 0x3e38aa3b, v202
	s_nop 0
	v_cndmask_b32_e32 v96, v77, v96, vcc
	v_fmamk_f32 v203, v203, 0x3fb8aa3b, v200
	v_cmp_le_i32_e32 vcc, 49, v198
	v_fmamk_f32 v97, v97, 0x3e38aa3b, v203
	s_nop 0
	v_cndmask_b32_e32 v97, v77, v97, vcc
	v_fmamk_f32 v228, v228, 0x3fb8aa3b, v200
	v_cmp_le_i32_e32 vcc, 50, v198
	v_fmamk_f32 v98, v98, 0x3e38aa3b, v228
	s_nop 0
	v_cndmask_b32_e32 v98, v77, v98, vcc
	v_fmamk_f32 v229, v229, 0x3fb8aa3b, v200
	v_cmp_le_i32_e32 vcc, 51, v198
	v_fmamk_f32 v99, v99, 0x3e38aa3b, v229
	s_nop 0
	v_cndmask_b32_e32 v99, v77, v99, vcc
	s_branch .Lbm2_Ag1_max

.Lbm2_Ag2_near:
	s_lshl_b32 s13, s54, 6
	s_sub_i32 s13, s97, s13
	s_add_i32 s13, s13, 8
	v_and_b32_e32 v245, 15, v181
	v_lshrrev_b32_e32 v246, 4, v181
	v_lshrrev_b32_e32 v245, 2, v245
	v_lshlrev_b32_e32 v246, 2, v246
	v_cndmask_b32_e32 v200, v77, v192, vcc
	v_sub_u32_e32 v245, v245, v246
	v_add_u32_e32 v198, s13, v245
	v_min_u32_e32 v82, 0x7f, v198
	v_lshl_add_u32 v82, v82, 2, v80
	ds_read_b32 v82, v82
	v_subrev_u32_e32 v245, 1, v198
	v_min_u32_e32 v83, 0x7f, v245
	v_lshl_add_u32 v83, v83, 2, v80
	ds_read_b32 v83, v83
	v_subrev_u32_e32 v245, 2, v198
	v_min_u32_e32 v172, 0x7f, v245
	v_lshl_add_u32 v172, v172, 2, v80
	ds_read_b32 v172, v172
	v_subrev_u32_e32 v245, 3, v198
	v_min_u32_e32 v173, 0x7f, v245
	v_lshl_add_u32 v173, v173, 2, v80
	ds_read_b32 v173, v173
	v_subrev_u32_e32 v245, 16, v198
	v_min_u32_e32 v202, 0x7f, v245
	v_lshl_add_u32 v202, v202, 2, v80
	ds_read_b32 v202, v202
	v_subrev_u32_e32 v245, 17, v198
	v_min_u32_e32 v203, 0x7f, v245
	v_lshl_add_u32 v203, v203, 2, v80
	ds_read_b32 v203, v203
	v_subrev_u32_e32 v245, 18, v198
	v_min_u32_e32 v228, 0x7f, v245
	v_lshl_add_u32 v228, v228, 2, v80
	ds_read_b32 v228, v228
	v_subrev_u32_e32 v245, 19, v198
	v_min_u32_e32 v229, 0x7f, v245
	v_lshl_add_u32 v229, v229, 2, v80
	ds_read_b32 v229, v229
	s_waitcnt lgkmcnt(0)
	v_fmamk_f32 v82, v82, 0x3fb8aa3b, v200
	v_cmp_le_i32_e32 vcc, 0, v198
	v_fmamk_f32 v84, v84, 0x3e38aa3b, v82
	s_nop 0
	v_cndmask_b32_e32 v84, v77, v84, vcc
	v_fmamk_f32 v83, v83, 0x3fb8aa3b, v200
	v_cmp_le_i32_e32 vcc, 1, v198
	v_fmamk_f32 v85, v85, 0x3e38aa3b, v83
	s_nop 0
	v_cndmask_b32_e32 v85, v77, v85, vcc
	v_fmamk_f32 v172, v172, 0x3fb8aa3b, v200
	v_cmp_le_i32_e32 vcc, 2, v198
	v_fmamk_f32 v86, v86, 0x3e38aa3b, v172
	s_nop 0
	v_cndmask_b32_e32 v86, v77, v86, vcc
	v_fmamk_f32 v173, v173, 0x3fb8aa3b, v200
	v_cmp_le_i32_e32 vcc, 3, v198
	v_fmamk_f32 v87, v87, 0x3e38aa3b, v173
	s_nop 0
	v_cndmask_b32_e32 v87, v77, v87, vcc
	v_fmamk_f32 v202, v202, 0x3fb8aa3b, v200
	v_cmp_le_i32_e32 vcc, 16, v198
	v_fmamk_f32 v88, v88, 0x3e38aa3b, v202
	s_nop 0
	v_cndmask_b32_e32 v88, v77, v88, vcc
	v_fmamk_f32 v203, v203, 0x3fb8aa3b, v200
	v_cmp_le_i32_e32 vcc, 17, v198
	v_fmamk_f32 v89, v89, 0x3e38aa3b, v203
	s_nop 0
	v_cndmask_b32_e32 v89, v77, v89, vcc
	v_fmamk_f32 v228, v228, 0x3fb8aa3b, v200
	v_cmp_le_i32_e32 vcc, 18, v198
	v_fmamk_f32 v90, v90, 0x3e38aa3b, v228
	s_nop 0
	v_cndmask_b32_e32 v90, v77, v90, vcc
	v_fmamk_f32 v229, v229, 0x3fb8aa3b, v200
	v_cmp_le_i32_e32 vcc, 19, v198
	v_fmamk_f32 v91, v91, 0x3e38aa3b, v229
	s_nop 0
	v_cndmask_b32_e32 v91, v77, v91, vcc
	v_subrev_u32_e32 v245, 32, v198
	v_min_u32_e32 v82, 0x7f, v245
	v_lshl_add_u32 v82, v82, 2, v80
	ds_read_b32 v82, v82
	v_subrev_u32_e32 v245, 33, v198
	v_min_u32_e32 v83, 0x7f, v245
	v_lshl_add_u32 v83, v83, 2, v80
	ds_read_b32 v83, v83
	v_subrev_u32_e32 v245, 34, v198
	v_min_u32_e32 v172, 0x7f, v245
	v_lshl_add_u32 v172, v172, 2, v80
	ds_read_b32 v172, v172
	v_subrev_u32_e32 v245, 35, v198
	v_min_u32_e32 v173, 0x7f, v245
	v_lshl_add_u32 v173, v173, 2, v80
	ds_read_b32 v173, v173
	v_subrev_u32_e32 v245, 48, v198
	v_min_u32_e32 v202, 0x7f, v245
	v_lshl_add_u32 v202, v202, 2, v80
	ds_read_b32 v202, v202
	v_subrev_u32_e32 v245, 49, v198
	v_min_u32_e32 v203, 0x7f, v245
	v_lshl_add_u32 v203, v203, 2, v80
	ds_read_b32 v203, v203
	v_subrev_u32_e32 v245, 50, v198
	v_min_u32_e32 v228, 0x7f, v245
	v_lshl_add_u32 v228, v228, 2, v80
	ds_read_b32 v228, v228
	v_subrev_u32_e32 v245, 51, v198
	v_min_u32_e32 v229, 0x7f, v245
	v_lshl_add_u32 v229, v229, 2, v80
	ds_read_b32 v229, v229
	s_waitcnt lgkmcnt(0)
	v_fmamk_f32 v82, v82, 0x3fb8aa3b, v200
	v_cmp_le_i32_e32 vcc, 32, v198
	v_fmamk_f32 v92, v92, 0x3e38aa3b, v82
	s_nop 0
	v_cndmask_b32_e32 v92, v77, v92, vcc
	v_fmamk_f32 v83, v83, 0x3fb8aa3b, v200
	v_cmp_le_i32_e32 vcc, 33, v198
	v_fmamk_f32 v93, v93, 0x3e38aa3b, v83
	s_nop 0
	v_cndmask_b32_e32 v93, v77, v93, vcc
	v_fmamk_f32 v172, v172, 0x3fb8aa3b, v200
	v_cmp_le_i32_e32 vcc, 34, v198
	v_fmamk_f32 v94, v94, 0x3e38aa3b, v172
	s_nop 0
	v_cndmask_b32_e32 v94, v77, v94, vcc
	v_fmamk_f32 v173, v173, 0x3fb8aa3b, v200
	v_cmp_le_i32_e32 vcc, 35, v198
	v_fmamk_f32 v95, v95, 0x3e38aa3b, v173
	s_nop 0
	v_cndmask_b32_e32 v95, v77, v95, vcc
	v_fmamk_f32 v202, v202, 0x3fb8aa3b, v200
	v_cmp_le_i32_e32 vcc, 48, v198
	v_fmamk_f32 v96, v96, 0x3e38aa3b, v202
	s_nop 0
	v_cndmask_b32_e32 v96, v77, v96, vcc
	v_fmamk_f32 v203, v203, 0x3fb8aa3b, v200
	v_cmp_le_i32_e32 vcc, 49, v198
	v_fmamk_f32 v97, v97, 0x3e38aa3b, v203
	s_nop 0
	v_cndmask_b32_e32 v97, v77, v97, vcc
	v_fmamk_f32 v228, v228, 0x3fb8aa3b, v200
	v_cmp_le_i32_e32 vcc, 50, v198
	v_fmamk_f32 v98, v98, 0x3e38aa3b, v228
	s_nop 0
	v_cndmask_b32_e32 v98, v77, v98, vcc
	v_fmamk_f32 v229, v229, 0x3fb8aa3b, v200
	v_cmp_le_i32_e32 vcc, 51, v198
	v_fmamk_f32 v99, v99, 0x3e38aa3b, v229
	s_nop 0
	v_cndmask_b32_e32 v99, v77, v99, vcc
	s_branch .Lbm2_Ag2_max

.Lbm2_Ag3_near:
	s_lshl_b32 s13, s54, 6
	s_sub_i32 s13, s97, s13
	s_add_i32 s13, s13, 12
	v_and_b32_e32 v245, 15, v181
	v_lshrrev_b32_e32 v246, 4, v181
	v_lshrrev_b32_e32 v245, 2, v245
	v_lshlrev_b32_e32 v246, 2, v246
	v_cndmask_b32_e32 v200, v77, v193, vcc
	v_sub_u32_e32 v245, v245, v246
	v_add_u32_e32 v198, s13, v245
	v_min_u32_e32 v82, 0x7f, v198
	v_lshl_add_u32 v82, v82, 2, v80
	ds_read_b32 v82, v82
	v_subrev_u32_e32 v245, 1, v198
	v_min_u32_e32 v83, 0x7f, v245
	v_lshl_add_u32 v83, v83, 2, v80
	ds_read_b32 v83, v83
	v_subrev_u32_e32 v245, 2, v198
	v_min_u32_e32 v172, 0x7f, v245
	v_lshl_add_u32 v172, v172, 2, v80
	ds_read_b32 v172, v172
	v_subrev_u32_e32 v245, 3, v198
	v_min_u32_e32 v173, 0x7f, v245
	v_lshl_add_u32 v173, v173, 2, v80
	ds_read_b32 v173, v173
	v_subrev_u32_e32 v245, 16, v198
	v_min_u32_e32 v202, 0x7f, v245
	v_lshl_add_u32 v202, v202, 2, v80
	ds_read_b32 v202, v202
	v_subrev_u32_e32 v245, 17, v198
	v_min_u32_e32 v203, 0x7f, v245
	v_lshl_add_u32 v203, v203, 2, v80
	ds_read_b32 v203, v203
	v_subrev_u32_e32 v245, 18, v198
	v_min_u32_e32 v228, 0x7f, v245
	v_lshl_add_u32 v228, v228, 2, v80
	ds_read_b32 v228, v228
	v_subrev_u32_e32 v245, 19, v198
	v_min_u32_e32 v229, 0x7f, v245
	v_lshl_add_u32 v229, v229, 2, v80
	ds_read_b32 v229, v229
	s_waitcnt lgkmcnt(0)
	v_fmamk_f32 v82, v82, 0x3fb8aa3b, v200
	v_cmp_le_i32_e32 vcc, 0, v198
	v_fmamk_f32 v84, v84, 0x3e38aa3b, v82
	s_nop 0
	v_cndmask_b32_e32 v84, v77, v84, vcc
	v_fmamk_f32 v83, v83, 0x3fb8aa3b, v200
	v_cmp_le_i32_e32 vcc, 1, v198
	v_fmamk_f32 v85, v85, 0x3e38aa3b, v83
	s_nop 0
	v_cndmask_b32_e32 v85, v77, v85, vcc
	v_fmamk_f32 v172, v172, 0x3fb8aa3b, v200
	v_cmp_le_i32_e32 vcc, 2, v198
	v_fmamk_f32 v86, v86, 0x3e38aa3b, v172
	s_nop 0
	v_cndmask_b32_e32 v86, v77, v86, vcc
	v_fmamk_f32 v173, v173, 0x3fb8aa3b, v200
	v_cmp_le_i32_e32 vcc, 3, v198
	v_fmamk_f32 v87, v87, 0x3e38aa3b, v173
	s_nop 0
	v_cndmask_b32_e32 v87, v77, v87, vcc
	v_fmamk_f32 v202, v202, 0x3fb8aa3b, v200
	v_cmp_le_i32_e32 vcc, 16, v198
	v_fmamk_f32 v88, v88, 0x3e38aa3b, v202
	s_nop 0
	v_cndmask_b32_e32 v88, v77, v88, vcc
	v_fmamk_f32 v203, v203, 0x3fb8aa3b, v200
	v_cmp_le_i32_e32 vcc, 17, v198
	v_fmamk_f32 v89, v89, 0x3e38aa3b, v203
	s_nop 0
	v_cndmask_b32_e32 v89, v77, v89, vcc
	v_fmamk_f32 v228, v228, 0x3fb8aa3b, v200
	v_cmp_le_i32_e32 vcc, 18, v198
	v_fmamk_f32 v90, v90, 0x3e38aa3b, v228
	s_nop 0
	v_cndmask_b32_e32 v90, v77, v90, vcc
	v_fmamk_f32 v229, v229, 0x3fb8aa3b, v200
	v_cmp_le_i32_e32 vcc, 19, v198
	v_fmamk_f32 v91, v91, 0x3e38aa3b, v229
	s_nop 0
	v_cndmask_b32_e32 v91, v77, v91, vcc
	v_subrev_u32_e32 v245, 32, v198
	v_min_u32_e32 v82, 0x7f, v245
	v_lshl_add_u32 v82, v82, 2, v80
	ds_read_b32 v82, v82
	v_subrev_u32_e32 v245, 33, v198
	v_min_u32_e32 v83, 0x7f, v245
	v_lshl_add_u32 v83, v83, 2, v80
	ds_read_b32 v83, v83
	v_subrev_u32_e32 v245, 34, v198
	v_min_u32_e32 v172, 0x7f, v245
	v_lshl_add_u32 v172, v172, 2, v80
	ds_read_b32 v172, v172
	v_subrev_u32_e32 v245, 35, v198
	v_min_u32_e32 v173, 0x7f, v245
	v_lshl_add_u32 v173, v173, 2, v80
	ds_read_b32 v173, v173
	v_subrev_u32_e32 v245, 48, v198
	v_min_u32_e32 v202, 0x7f, v245
	v_lshl_add_u32 v202, v202, 2, v80
	ds_read_b32 v202, v202
	v_subrev_u32_e32 v245, 49, v198
	v_min_u32_e32 v203, 0x7f, v245
	v_lshl_add_u32 v203, v203, 2, v80
	ds_read_b32 v203, v203
	v_subrev_u32_e32 v245, 50, v198
	v_min_u32_e32 v228, 0x7f, v245
	v_lshl_add_u32 v228, v228, 2, v80
	ds_read_b32 v228, v228
	v_subrev_u32_e32 v245, 51, v198
	v_min_u32_e32 v229, 0x7f, v245
	v_lshl_add_u32 v229, v229, 2, v80
	ds_read_b32 v229, v229
	s_waitcnt lgkmcnt(0)
	v_fmamk_f32 v82, v82, 0x3fb8aa3b, v200
	v_cmp_le_i32_e32 vcc, 32, v198
	v_fmamk_f32 v92, v92, 0x3e38aa3b, v82
	s_nop 0
	v_cndmask_b32_e32 v92, v77, v92, vcc
	v_fmamk_f32 v83, v83, 0x3fb8aa3b, v200
	v_cmp_le_i32_e32 vcc, 33, v198
	v_fmamk_f32 v93, v93, 0x3e38aa3b, v83
	s_nop 0
	v_cndmask_b32_e32 v93, v77, v93, vcc
	v_fmamk_f32 v172, v172, 0x3fb8aa3b, v200
	v_cmp_le_i32_e32 vcc, 34, v198
	v_fmamk_f32 v94, v94, 0x3e38aa3b, v172
	s_nop 0
	v_cndmask_b32_e32 v94, v77, v94, vcc
	v_fmamk_f32 v173, v173, 0x3fb8aa3b, v200
	v_cmp_le_i32_e32 vcc, 35, v198
	v_fmamk_f32 v95, v95, 0x3e38aa3b, v173
	s_nop 0
	v_cndmask_b32_e32 v95, v77, v95, vcc
	v_fmamk_f32 v202, v202, 0x3fb8aa3b, v200
	v_cmp_le_i32_e32 vcc, 48, v198
	v_fmamk_f32 v96, v96, 0x3e38aa3b, v202
	s_nop 0
	v_cndmask_b32_e32 v96, v77, v96, vcc
	v_fmamk_f32 v203, v203, 0x3fb8aa3b, v200
	v_cmp_le_i32_e32 vcc, 49, v198
	v_fmamk_f32 v97, v97, 0x3e38aa3b, v203
	s_nop 0
	v_cndmask_b32_e32 v97, v77, v97, vcc
	v_fmamk_f32 v228, v228, 0x3fb8aa3b, v200
	v_cmp_le_i32_e32 vcc, 50, v198
	v_fmamk_f32 v98, v98, 0x3e38aa3b, v228
	s_nop 0
	v_cndmask_b32_e32 v98, v77, v98, vcc
	v_fmamk_f32 v229, v229, 0x3fb8aa3b, v200
	v_cmp_le_i32_e32 vcc, 51, v198
	v_fmamk_f32 v99, v99, 0x3e38aa3b, v229
	s_nop 0
	v_cndmask_b32_e32 v99, v77, v99, vcc
	s_branch .Lbm2_Ag3_max

.Lbm3_Ag0_near:
	s_lshl_b32 s9, s38, 6
	s_sub_i32 s9, s47, s9
	v_and_b32_e32 v245, 15, v181
	v_lshrrev_b32_e32 v246, 4, v181
	v_lshrrev_b32_e32 v245, 2, v245
	v_lshlrev_b32_e32 v246, 2, v246
	v_cndmask_b32_e32 v200, v77, v190, vcc
	v_sub_u32_e32 v245, v245, v246
	v_add_u32_e32 v198, s9, v245
	v_min_u32_e32 v82, 0x7f, v198
	v_lshl_add_u32 v82, v82, 2, v80
	ds_read_b32 v82, v82
	v_subrev_u32_e32 v245, 1, v198
	v_min_u32_e32 v83, 0x7f, v245
	v_lshl_add_u32 v83, v83, 2, v80
	ds_read_b32 v83, v83
	v_subrev_u32_e32 v245, 2, v198
	v_min_u32_e32 v172, 0x7f, v245
	v_lshl_add_u32 v172, v172, 2, v80
	ds_read_b32 v172, v172
	v_subrev_u32_e32 v245, 3, v198
	v_min_u32_e32 v173, 0x7f, v245
	v_lshl_add_u32 v173, v173, 2, v80
	ds_read_b32 v173, v173
	v_subrev_u32_e32 v245, 16, v198
	v_min_u32_e32 v202, 0x7f, v245
	v_lshl_add_u32 v202, v202, 2, v80
	ds_read_b32 v202, v202
	v_subrev_u32_e32 v245, 17, v198
	v_min_u32_e32 v203, 0x7f, v245
	v_lshl_add_u32 v203, v203, 2, v80
	ds_read_b32 v203, v203
	v_subrev_u32_e32 v245, 18, v198
	v_min_u32_e32 v228, 0x7f, v245
	v_lshl_add_u32 v228, v228, 2, v80
	ds_read_b32 v228, v228
	v_subrev_u32_e32 v245, 19, v198
	v_min_u32_e32 v229, 0x7f, v245
	v_lshl_add_u32 v229, v229, 2, v80
	ds_read_b32 v229, v229
	s_waitcnt lgkmcnt(0)
	v_fmamk_f32 v82, v82, 0x3fb8aa3b, v200
	v_cmp_le_i32_e32 vcc, 0, v198
	v_fmamk_f32 v84, v84, 0x3e38aa3b, v82
	s_nop 0
	v_cndmask_b32_e32 v84, v77, v84, vcc
	v_fmamk_f32 v83, v83, 0x3fb8aa3b, v200
	v_cmp_le_i32_e32 vcc, 1, v198
	v_fmamk_f32 v85, v85, 0x3e38aa3b, v83
	s_nop 0
	v_cndmask_b32_e32 v85, v77, v85, vcc
	v_fmamk_f32 v172, v172, 0x3fb8aa3b, v200
	v_cmp_le_i32_e32 vcc, 2, v198
	v_fmamk_f32 v86, v86, 0x3e38aa3b, v172
	s_nop 0
	v_cndmask_b32_e32 v86, v77, v86, vcc
	v_fmamk_f32 v173, v173, 0x3fb8aa3b, v200
	v_cmp_le_i32_e32 vcc, 3, v198
	v_fmamk_f32 v87, v87, 0x3e38aa3b, v173
	s_nop 0
	v_cndmask_b32_e32 v87, v77, v87, vcc
	v_fmamk_f32 v202, v202, 0x3fb8aa3b, v200
	v_cmp_le_i32_e32 vcc, 16, v198
	v_fmamk_f32 v88, v88, 0x3e38aa3b, v202
	s_nop 0
	v_cndmask_b32_e32 v88, v77, v88, vcc
	v_fmamk_f32 v203, v203, 0x3fb8aa3b, v200
	v_cmp_le_i32_e32 vcc, 17, v198
	v_fmamk_f32 v89, v89, 0x3e38aa3b, v203
	s_nop 0
	v_cndmask_b32_e32 v89, v77, v89, vcc
	v_fmamk_f32 v228, v228, 0x3fb8aa3b, v200
	v_cmp_le_i32_e32 vcc, 18, v198
	v_fmamk_f32 v90, v90, 0x3e38aa3b, v228
	s_nop 0
	v_cndmask_b32_e32 v90, v77, v90, vcc
	v_fmamk_f32 v229, v229, 0x3fb8aa3b, v200
	v_cmp_le_i32_e32 vcc, 19, v198
	v_fmamk_f32 v91, v91, 0x3e38aa3b, v229
	s_nop 0
	v_cndmask_b32_e32 v91, v77, v91, vcc
	v_subrev_u32_e32 v245, 32, v198
	v_min_u32_e32 v82, 0x7f, v245
	v_lshl_add_u32 v82, v82, 2, v80
	ds_read_b32 v82, v82
	v_subrev_u32_e32 v245, 33, v198
	v_min_u32_e32 v83, 0x7f, v245
	v_lshl_add_u32 v83, v83, 2, v80
	ds_read_b32 v83, v83
	v_subrev_u32_e32 v245, 34, v198
	v_min_u32_e32 v172, 0x7f, v245
	v_lshl_add_u32 v172, v172, 2, v80
	ds_read_b32 v172, v172
	v_subrev_u32_e32 v245, 35, v198
	v_min_u32_e32 v173, 0x7f, v245
	v_lshl_add_u32 v173, v173, 2, v80
	ds_read_b32 v173, v173
	v_subrev_u32_e32 v245, 48, v198
	v_min_u32_e32 v202, 0x7f, v245
	v_lshl_add_u32 v202, v202, 2, v80
	ds_read_b32 v202, v202
	v_subrev_u32_e32 v245, 49, v198
	v_min_u32_e32 v203, 0x7f, v245
	v_lshl_add_u32 v203, v203, 2, v80
	ds_read_b32 v203, v203
	v_subrev_u32_e32 v245, 50, v198
	v_min_u32_e32 v228, 0x7f, v245
	v_lshl_add_u32 v228, v228, 2, v80
	ds_read_b32 v228, v228
	v_subrev_u32_e32 v245, 51, v198
	v_min_u32_e32 v229, 0x7f, v245
	v_lshl_add_u32 v229, v229, 2, v80
	ds_read_b32 v229, v229
	s_waitcnt lgkmcnt(0)
	v_fmamk_f32 v82, v82, 0x3fb8aa3b, v200
	v_cmp_le_i32_e32 vcc, 32, v198
	v_fmamk_f32 v92, v92, 0x3e38aa3b, v82
	s_nop 0
	v_cndmask_b32_e32 v92, v77, v92, vcc
	v_fmamk_f32 v83, v83, 0x3fb8aa3b, v200
	v_cmp_le_i32_e32 vcc, 33, v198
	v_fmamk_f32 v93, v93, 0x3e38aa3b, v83
	s_nop 0
	v_cndmask_b32_e32 v93, v77, v93, vcc
	v_fmamk_f32 v172, v172, 0x3fb8aa3b, v200
	v_cmp_le_i32_e32 vcc, 34, v198
	v_fmamk_f32 v94, v94, 0x3e38aa3b, v172
	s_nop 0
	v_cndmask_b32_e32 v94, v77, v94, vcc
	v_fmamk_f32 v173, v173, 0x3fb8aa3b, v200
	v_cmp_le_i32_e32 vcc, 35, v198
	v_fmamk_f32 v95, v95, 0x3e38aa3b, v173
	s_nop 0
	v_cndmask_b32_e32 v95, v77, v95, vcc
	v_fmamk_f32 v202, v202, 0x3fb8aa3b, v200
	v_cmp_le_i32_e32 vcc, 48, v198
	v_fmamk_f32 v96, v96, 0x3e38aa3b, v202
	s_nop 0
	v_cndmask_b32_e32 v96, v77, v96, vcc
	v_fmamk_f32 v203, v203, 0x3fb8aa3b, v200
	v_cmp_le_i32_e32 vcc, 49, v198
	v_fmamk_f32 v97, v97, 0x3e38aa3b, v203
	s_nop 0
	v_cndmask_b32_e32 v97, v77, v97, vcc
	v_fmamk_f32 v228, v228, 0x3fb8aa3b, v200
	v_cmp_le_i32_e32 vcc, 50, v198
	v_fmamk_f32 v98, v98, 0x3e38aa3b, v228
	s_nop 0
	v_cndmask_b32_e32 v98, v77, v98, vcc
	v_fmamk_f32 v229, v229, 0x3fb8aa3b, v200
	v_cmp_le_i32_e32 vcc, 51, v198
	v_fmamk_f32 v99, v99, 0x3e38aa3b, v229
	s_nop 0
	v_cndmask_b32_e32 v99, v77, v99, vcc
	s_branch .Lbm3_Ag0_max

.Lbm3_Ag1_near:
	s_lshl_b32 s9, s38, 6
	s_sub_i32 s9, s47, s9
	s_add_i32 s9, s9, 4
	v_and_b32_e32 v245, 15, v181
	v_lshrrev_b32_e32 v246, 4, v181
	v_lshrrev_b32_e32 v245, 2, v245
	v_lshlrev_b32_e32 v246, 2, v246
	v_cndmask_b32_e32 v200, v77, v191, vcc
	v_sub_u32_e32 v245, v245, v246
	v_add_u32_e32 v198, s9, v245
	v_min_u32_e32 v82, 0x7f, v198
	v_lshl_add_u32 v82, v82, 2, v80
	ds_read_b32 v82, v82
	v_subrev_u32_e32 v245, 1, v198
	v_min_u32_e32 v83, 0x7f, v245
	v_lshl_add_u32 v83, v83, 2, v80
	ds_read_b32 v83, v83
	v_subrev_u32_e32 v245, 2, v198
	v_min_u32_e32 v172, 0x7f, v245
	v_lshl_add_u32 v172, v172, 2, v80
	ds_read_b32 v172, v172
	v_subrev_u32_e32 v245, 3, v198
	v_min_u32_e32 v173, 0x7f, v245
	v_lshl_add_u32 v173, v173, 2, v80
	ds_read_b32 v173, v173
	v_subrev_u32_e32 v245, 16, v198
	v_min_u32_e32 v202, 0x7f, v245
	v_lshl_add_u32 v202, v202, 2, v80
	ds_read_b32 v202, v202
	v_subrev_u32_e32 v245, 17, v198
	v_min_u32_e32 v203, 0x7f, v245
	v_lshl_add_u32 v203, v203, 2, v80
	ds_read_b32 v203, v203
	v_subrev_u32_e32 v245, 18, v198
	v_min_u32_e32 v228, 0x7f, v245
	v_lshl_add_u32 v228, v228, 2, v80
	ds_read_b32 v228, v228
	v_subrev_u32_e32 v245, 19, v198
	v_min_u32_e32 v229, 0x7f, v245
	v_lshl_add_u32 v229, v229, 2, v80
	ds_read_b32 v229, v229
	s_waitcnt lgkmcnt(0)
	v_fmamk_f32 v82, v82, 0x3fb8aa3b, v200
	v_cmp_le_i32_e32 vcc, 0, v198
	v_fmamk_f32 v84, v84, 0x3e38aa3b, v82
	s_nop 0
	v_cndmask_b32_e32 v84, v77, v84, vcc
	v_fmamk_f32 v83, v83, 0x3fb8aa3b, v200
	v_cmp_le_i32_e32 vcc, 1, v198
	v_fmamk_f32 v85, v85, 0x3e38aa3b, v83
	s_nop 0
	v_cndmask_b32_e32 v85, v77, v85, vcc
	v_fmamk_f32 v172, v172, 0x3fb8aa3b, v200
	v_cmp_le_i32_e32 vcc, 2, v198
	v_fmamk_f32 v86, v86, 0x3e38aa3b, v172
	s_nop 0
	v_cndmask_b32_e32 v86, v77, v86, vcc
	v_fmamk_f32 v173, v173, 0x3fb8aa3b, v200
	v_cmp_le_i32_e32 vcc, 3, v198
	v_fmamk_f32 v87, v87, 0x3e38aa3b, v173
	s_nop 0
	v_cndmask_b32_e32 v87, v77, v87, vcc
	v_fmamk_f32 v202, v202, 0x3fb8aa3b, v200
	v_cmp_le_i32_e32 vcc, 16, v198
	v_fmamk_f32 v88, v88, 0x3e38aa3b, v202
	s_nop 0
	v_cndmask_b32_e32 v88, v77, v88, vcc
	v_fmamk_f32 v203, v203, 0x3fb8aa3b, v200
	v_cmp_le_i32_e32 vcc, 17, v198
	v_fmamk_f32 v89, v89, 0x3e38aa3b, v203
	s_nop 0
	v_cndmask_b32_e32 v89, v77, v89, vcc
	v_fmamk_f32 v228, v228, 0x3fb8aa3b, v200
	v_cmp_le_i32_e32 vcc, 18, v198
	v_fmamk_f32 v90, v90, 0x3e38aa3b, v228
	s_nop 0
	v_cndmask_b32_e32 v90, v77, v90, vcc
	v_fmamk_f32 v229, v229, 0x3fb8aa3b, v200
	v_cmp_le_i32_e32 vcc, 19, v198
	v_fmamk_f32 v91, v91, 0x3e38aa3b, v229
	s_nop 0
	v_cndmask_b32_e32 v91, v77, v91, vcc
	v_subrev_u32_e32 v245, 32, v198
	v_min_u32_e32 v82, 0x7f, v245
	v_lshl_add_u32 v82, v82, 2, v80
	ds_read_b32 v82, v82
	v_subrev_u32_e32 v245, 33, v198
	v_min_u32_e32 v83, 0x7f, v245
	v_lshl_add_u32 v83, v83, 2, v80
	ds_read_b32 v83, v83
	v_subrev_u32_e32 v245, 34, v198
	v_min_u32_e32 v172, 0x7f, v245
	v_lshl_add_u32 v172, v172, 2, v80
	ds_read_b32 v172, v172
	v_subrev_u32_e32 v245, 35, v198
	v_min_u32_e32 v173, 0x7f, v245
	v_lshl_add_u32 v173, v173, 2, v80
	ds_read_b32 v173, v173
	v_subrev_u32_e32 v245, 48, v198
	v_min_u32_e32 v202, 0x7f, v245
	v_lshl_add_u32 v202, v202, 2, v80
	ds_read_b32 v202, v202
	v_subrev_u32_e32 v245, 49, v198
	v_min_u32_e32 v203, 0x7f, v245
	v_lshl_add_u32 v203, v203, 2, v80
	ds_read_b32 v203, v203
	v_subrev_u32_e32 v245, 50, v198
	v_min_u32_e32 v228, 0x7f, v245
	v_lshl_add_u32 v228, v228, 2, v80
	ds_read_b32 v228, v228
	v_subrev_u32_e32 v245, 51, v198
	v_min_u32_e32 v229, 0x7f, v245
	v_lshl_add_u32 v229, v229, 2, v80
	ds_read_b32 v229, v229
	s_waitcnt lgkmcnt(0)
	v_fmamk_f32 v82, v82, 0x3fb8aa3b, v200
	v_cmp_le_i32_e32 vcc, 32, v198
	v_fmamk_f32 v92, v92, 0x3e38aa3b, v82
	s_nop 0
	v_cndmask_b32_e32 v92, v77, v92, vcc
	v_fmamk_f32 v83, v83, 0x3fb8aa3b, v200
	v_cmp_le_i32_e32 vcc, 33, v198
	v_fmamk_f32 v93, v93, 0x3e38aa3b, v83
	s_nop 0
	v_cndmask_b32_e32 v93, v77, v93, vcc
	v_fmamk_f32 v172, v172, 0x3fb8aa3b, v200
	v_cmp_le_i32_e32 vcc, 34, v198
	v_fmamk_f32 v94, v94, 0x3e38aa3b, v172
	s_nop 0
	v_cndmask_b32_e32 v94, v77, v94, vcc
	v_fmamk_f32 v173, v173, 0x3fb8aa3b, v200
	v_cmp_le_i32_e32 vcc, 35, v198
	v_fmamk_f32 v95, v95, 0x3e38aa3b, v173
	s_nop 0
	v_cndmask_b32_e32 v95, v77, v95, vcc
	v_fmamk_f32 v202, v202, 0x3fb8aa3b, v200
	v_cmp_le_i32_e32 vcc, 48, v198
	v_fmamk_f32 v96, v96, 0x3e38aa3b, v202
	s_nop 0
	v_cndmask_b32_e32 v96, v77, v96, vcc
	v_fmamk_f32 v203, v203, 0x3fb8aa3b, v200
	v_cmp_le_i32_e32 vcc, 49, v198
	v_fmamk_f32 v97, v97, 0x3e38aa3b, v203
	s_nop 0
	v_cndmask_b32_e32 v97, v77, v97, vcc
	v_fmamk_f32 v228, v228, 0x3fb8aa3b, v200
	v_cmp_le_i32_e32 vcc, 50, v198
	v_fmamk_f32 v98, v98, 0x3e38aa3b, v228
	s_nop 0
	v_cndmask_b32_e32 v98, v77, v98, vcc
	v_fmamk_f32 v229, v229, 0x3fb8aa3b, v200
	v_cmp_le_i32_e32 vcc, 51, v198
	v_fmamk_f32 v99, v99, 0x3e38aa3b, v229
	s_nop 0
	v_cndmask_b32_e32 v99, v77, v99, vcc
	s_branch .Lbm3_Ag1_max

.Lbm3_Ag2_near:
	s_lshl_b32 s9, s38, 6
	s_sub_i32 s9, s47, s9
	s_add_i32 s9, s9, 8
	v_and_b32_e32 v245, 15, v181
	v_lshrrev_b32_e32 v246, 4, v181
	v_lshrrev_b32_e32 v245, 2, v245
	v_lshlrev_b32_e32 v246, 2, v246
	v_cndmask_b32_e32 v200, v77, v192, vcc
	v_sub_u32_e32 v245, v245, v246
	v_add_u32_e32 v198, s9, v245
	v_min_u32_e32 v82, 0x7f, v198
	v_lshl_add_u32 v82, v82, 2, v80
	ds_read_b32 v82, v82
	v_subrev_u32_e32 v245, 1, v198
	v_min_u32_e32 v83, 0x7f, v245
	v_lshl_add_u32 v83, v83, 2, v80
	ds_read_b32 v83, v83
	v_subrev_u32_e32 v245, 2, v198
	v_min_u32_e32 v172, 0x7f, v245
	v_lshl_add_u32 v172, v172, 2, v80
	ds_read_b32 v172, v172
	v_subrev_u32_e32 v245, 3, v198
	v_min_u32_e32 v173, 0x7f, v245
	v_lshl_add_u32 v173, v173, 2, v80
	ds_read_b32 v173, v173
	v_subrev_u32_e32 v245, 16, v198
	v_min_u32_e32 v202, 0x7f, v245
	v_lshl_add_u32 v202, v202, 2, v80
	ds_read_b32 v202, v202
	v_subrev_u32_e32 v245, 17, v198
	v_min_u32_e32 v203, 0x7f, v245
	v_lshl_add_u32 v203, v203, 2, v80
	ds_read_b32 v203, v203
	v_subrev_u32_e32 v245, 18, v198
	v_min_u32_e32 v228, 0x7f, v245
	v_lshl_add_u32 v228, v228, 2, v80
	ds_read_b32 v228, v228
	v_subrev_u32_e32 v245, 19, v198
	v_min_u32_e32 v229, 0x7f, v245
	v_lshl_add_u32 v229, v229, 2, v80
	ds_read_b32 v229, v229
	s_waitcnt lgkmcnt(0)
	v_fmamk_f32 v82, v82, 0x3fb8aa3b, v200
	v_cmp_le_i32_e32 vcc, 0, v198
	v_fmamk_f32 v84, v84, 0x3e38aa3b, v82
	s_nop 0
	v_cndmask_b32_e32 v84, v77, v84, vcc
	v_fmamk_f32 v83, v83, 0x3fb8aa3b, v200
	v_cmp_le_i32_e32 vcc, 1, v198
	v_fmamk_f32 v85, v85, 0x3e38aa3b, v83
	s_nop 0
	v_cndmask_b32_e32 v85, v77, v85, vcc
	v_fmamk_f32 v172, v172, 0x3fb8aa3b, v200
	v_cmp_le_i32_e32 vcc, 2, v198
	v_fmamk_f32 v86, v86, 0x3e38aa3b, v172
	s_nop 0
	v_cndmask_b32_e32 v86, v77, v86, vcc
	v_fmamk_f32 v173, v173, 0x3fb8aa3b, v200
	v_cmp_le_i32_e32 vcc, 3, v198
	v_fmamk_f32 v87, v87, 0x3e38aa3b, v173
	s_nop 0
	v_cndmask_b32_e32 v87, v77, v87, vcc
	v_fmamk_f32 v202, v202, 0x3fb8aa3b, v200
	v_cmp_le_i32_e32 vcc, 16, v198
	v_fmamk_f32 v88, v88, 0x3e38aa3b, v202
	s_nop 0
	v_cndmask_b32_e32 v88, v77, v88, vcc
	v_fmamk_f32 v203, v203, 0x3fb8aa3b, v200
	v_cmp_le_i32_e32 vcc, 17, v198
	v_fmamk_f32 v89, v89, 0x3e38aa3b, v203
	s_nop 0
	v_cndmask_b32_e32 v89, v77, v89, vcc
	v_fmamk_f32 v228, v228, 0x3fb8aa3b, v200
	v_cmp_le_i32_e32 vcc, 18, v198
	v_fmamk_f32 v90, v90, 0x3e38aa3b, v228
	s_nop 0
	v_cndmask_b32_e32 v90, v77, v90, vcc
	v_fmamk_f32 v229, v229, 0x3fb8aa3b, v200
	v_cmp_le_i32_e32 vcc, 19, v198
	v_fmamk_f32 v91, v91, 0x3e38aa3b, v229
	s_nop 0
	v_cndmask_b32_e32 v91, v77, v91, vcc
	v_subrev_u32_e32 v245, 32, v198
	v_min_u32_e32 v82, 0x7f, v245
	v_lshl_add_u32 v82, v82, 2, v80
	ds_read_b32 v82, v82
	v_subrev_u32_e32 v245, 33, v198
	v_min_u32_e32 v83, 0x7f, v245
	v_lshl_add_u32 v83, v83, 2, v80
	ds_read_b32 v83, v83
	v_subrev_u32_e32 v245, 34, v198
	v_min_u32_e32 v172, 0x7f, v245
	v_lshl_add_u32 v172, v172, 2, v80
	ds_read_b32 v172, v172
	v_subrev_u32_e32 v245, 35, v198
	v_min_u32_e32 v173, 0x7f, v245
	v_lshl_add_u32 v173, v173, 2, v80
	ds_read_b32 v173, v173
	v_subrev_u32_e32 v245, 48, v198
	v_min_u32_e32 v202, 0x7f, v245
	v_lshl_add_u32 v202, v202, 2, v80
	ds_read_b32 v202, v202
	v_subrev_u32_e32 v245, 49, v198
	v_min_u32_e32 v203, 0x7f, v245
	v_lshl_add_u32 v203, v203, 2, v80
	ds_read_b32 v203, v203
	v_subrev_u32_e32 v245, 50, v198
	v_min_u32_e32 v228, 0x7f, v245
	v_lshl_add_u32 v228, v228, 2, v80
	ds_read_b32 v228, v228
	v_subrev_u32_e32 v245, 51, v198
	v_min_u32_e32 v229, 0x7f, v245
	v_lshl_add_u32 v229, v229, 2, v80
	ds_read_b32 v229, v229
	s_waitcnt lgkmcnt(0)
	v_fmamk_f32 v82, v82, 0x3fb8aa3b, v200
	v_cmp_le_i32_e32 vcc, 32, v198
	v_fmamk_f32 v92, v92, 0x3e38aa3b, v82
	s_nop 0
	v_cndmask_b32_e32 v92, v77, v92, vcc
	v_fmamk_f32 v83, v83, 0x3fb8aa3b, v200
	v_cmp_le_i32_e32 vcc, 33, v198
	v_fmamk_f32 v93, v93, 0x3e38aa3b, v83
	s_nop 0
	v_cndmask_b32_e32 v93, v77, v93, vcc
	v_fmamk_f32 v172, v172, 0x3fb8aa3b, v200
	v_cmp_le_i32_e32 vcc, 34, v198
	v_fmamk_f32 v94, v94, 0x3e38aa3b, v172
	s_nop 0
	v_cndmask_b32_e32 v94, v77, v94, vcc
	v_fmamk_f32 v173, v173, 0x3fb8aa3b, v200
	v_cmp_le_i32_e32 vcc, 35, v198
	v_fmamk_f32 v95, v95, 0x3e38aa3b, v173
	s_nop 0
	v_cndmask_b32_e32 v95, v77, v95, vcc
	v_fmamk_f32 v202, v202, 0x3fb8aa3b, v200
	v_cmp_le_i32_e32 vcc, 48, v198
	v_fmamk_f32 v96, v96, 0x3e38aa3b, v202
	s_nop 0
	v_cndmask_b32_e32 v96, v77, v96, vcc
	v_fmamk_f32 v203, v203, 0x3fb8aa3b, v200
	v_cmp_le_i32_e32 vcc, 49, v198
	v_fmamk_f32 v97, v97, 0x3e38aa3b, v203
	s_nop 0
	v_cndmask_b32_e32 v97, v77, v97, vcc
	v_fmamk_f32 v228, v228, 0x3fb8aa3b, v200
	v_cmp_le_i32_e32 vcc, 50, v198
	v_fmamk_f32 v98, v98, 0x3e38aa3b, v228
	s_nop 0
	v_cndmask_b32_e32 v98, v77, v98, vcc
	v_fmamk_f32 v229, v229, 0x3fb8aa3b, v200
	v_cmp_le_i32_e32 vcc, 51, v198
	v_fmamk_f32 v99, v99, 0x3e38aa3b, v229
	s_nop 0
	v_cndmask_b32_e32 v99, v77, v99, vcc
	s_branch .Lbm3_Ag2_max

.Lbm3_Ag3_near:
	s_lshl_b32 s9, s38, 6
	s_sub_i32 s9, s47, s9
	s_add_i32 s9, s9, 12
	v_and_b32_e32 v245, 15, v181
	v_lshrrev_b32_e32 v246, 4, v181
	v_lshrrev_b32_e32 v245, 2, v245
	v_lshlrev_b32_e32 v246, 2, v246
	v_cndmask_b32_e32 v200, v77, v193, vcc
	v_sub_u32_e32 v245, v245, v246
	v_add_u32_e32 v198, s9, v245
	v_min_u32_e32 v82, 0x7f, v198
	v_lshl_add_u32 v82, v82, 2, v80
	ds_read_b32 v82, v82
	v_subrev_u32_e32 v245, 1, v198
	v_min_u32_e32 v83, 0x7f, v245
	v_lshl_add_u32 v83, v83, 2, v80
	ds_read_b32 v83, v83
	v_subrev_u32_e32 v245, 2, v198
	v_min_u32_e32 v172, 0x7f, v245
	v_lshl_add_u32 v172, v172, 2, v80
	ds_read_b32 v172, v172
	v_subrev_u32_e32 v245, 3, v198
	v_min_u32_e32 v173, 0x7f, v245
	v_lshl_add_u32 v173, v173, 2, v80
	ds_read_b32 v173, v173
	v_subrev_u32_e32 v245, 16, v198
	v_min_u32_e32 v202, 0x7f, v245
	v_lshl_add_u32 v202, v202, 2, v80
	ds_read_b32 v202, v202
	v_subrev_u32_e32 v245, 17, v198
	v_min_u32_e32 v203, 0x7f, v245
	v_lshl_add_u32 v203, v203, 2, v80
	ds_read_b32 v203, v203
	v_subrev_u32_e32 v245, 18, v198
	v_min_u32_e32 v228, 0x7f, v245
	v_lshl_add_u32 v228, v228, 2, v80
	ds_read_b32 v228, v228
	v_subrev_u32_e32 v245, 19, v198
	v_min_u32_e32 v229, 0x7f, v245
	v_lshl_add_u32 v229, v229, 2, v80
	ds_read_b32 v229, v229
	s_waitcnt lgkmcnt(0)
	v_fmamk_f32 v82, v82, 0x3fb8aa3b, v200
	v_cmp_le_i32_e32 vcc, 0, v198
	v_fmamk_f32 v84, v84, 0x3e38aa3b, v82
	s_nop 0
	v_cndmask_b32_e32 v84, v77, v84, vcc
	v_fmamk_f32 v83, v83, 0x3fb8aa3b, v200
	v_cmp_le_i32_e32 vcc, 1, v198
	v_fmamk_f32 v85, v85, 0x3e38aa3b, v83
	s_nop 0
	v_cndmask_b32_e32 v85, v77, v85, vcc
	v_fmamk_f32 v172, v172, 0x3fb8aa3b, v200
	v_cmp_le_i32_e32 vcc, 2, v198
	v_fmamk_f32 v86, v86, 0x3e38aa3b, v172
	s_nop 0
	v_cndmask_b32_e32 v86, v77, v86, vcc
	v_fmamk_f32 v173, v173, 0x3fb8aa3b, v200
	v_cmp_le_i32_e32 vcc, 3, v198
	v_fmamk_f32 v87, v87, 0x3e38aa3b, v173
	s_nop 0
	v_cndmask_b32_e32 v87, v77, v87, vcc
	v_fmamk_f32 v202, v202, 0x3fb8aa3b, v200
	v_cmp_le_i32_e32 vcc, 16, v198
	v_fmamk_f32 v88, v88, 0x3e38aa3b, v202
	s_nop 0
	v_cndmask_b32_e32 v88, v77, v88, vcc
	v_fmamk_f32 v203, v203, 0x3fb8aa3b, v200
	v_cmp_le_i32_e32 vcc, 17, v198
	v_fmamk_f32 v89, v89, 0x3e38aa3b, v203
	s_nop 0
	v_cndmask_b32_e32 v89, v77, v89, vcc
	v_fmamk_f32 v228, v228, 0x3fb8aa3b, v200
	v_cmp_le_i32_e32 vcc, 18, v198
	v_fmamk_f32 v90, v90, 0x3e38aa3b, v228
	s_nop 0
	v_cndmask_b32_e32 v90, v77, v90, vcc
	v_fmamk_f32 v229, v229, 0x3fb8aa3b, v200
	v_cmp_le_i32_e32 vcc, 19, v198
	v_fmamk_f32 v91, v91, 0x3e38aa3b, v229
	s_nop 0
	v_cndmask_b32_e32 v91, v77, v91, vcc
	v_subrev_u32_e32 v245, 32, v198
	v_min_u32_e32 v82, 0x7f, v245
	v_lshl_add_u32 v82, v82, 2, v80
	ds_read_b32 v82, v82
	v_subrev_u32_e32 v245, 33, v198
	v_min_u32_e32 v83, 0x7f, v245
	v_lshl_add_u32 v83, v83, 2, v80
	ds_read_b32 v83, v83
	v_subrev_u32_e32 v245, 34, v198
	v_min_u32_e32 v172, 0x7f, v245
	v_lshl_add_u32 v172, v172, 2, v80
	ds_read_b32 v172, v172
	v_subrev_u32_e32 v245, 35, v198
	v_min_u32_e32 v173, 0x7f, v245
	v_lshl_add_u32 v173, v173, 2, v80
	ds_read_b32 v173, v173
	v_subrev_u32_e32 v245, 48, v198
	v_min_u32_e32 v202, 0x7f, v245
	v_lshl_add_u32 v202, v202, 2, v80
	ds_read_b32 v202, v202
	v_subrev_u32_e32 v245, 49, v198
	v_min_u32_e32 v203, 0x7f, v245
	v_lshl_add_u32 v203, v203, 2, v80
	ds_read_b32 v203, v203
	v_subrev_u32_e32 v245, 50, v198
	v_min_u32_e32 v228, 0x7f, v245
	v_lshl_add_u32 v228, v228, 2, v80
	ds_read_b32 v228, v228
	v_subrev_u32_e32 v245, 51, v198
	v_min_u32_e32 v229, 0x7f, v245
	v_lshl_add_u32 v229, v229, 2, v80
	ds_read_b32 v229, v229
	s_waitcnt lgkmcnt(0)
	v_fmamk_f32 v82, v82, 0x3fb8aa3b, v200
	v_cmp_le_i32_e32 vcc, 32, v198
	v_fmamk_f32 v92, v92, 0x3e38aa3b, v82
	s_nop 0
	v_cndmask_b32_e32 v92, v77, v92, vcc
	v_fmamk_f32 v83, v83, 0x3fb8aa3b, v200
	v_cmp_le_i32_e32 vcc, 33, v198
	v_fmamk_f32 v93, v93, 0x3e38aa3b, v83
	s_nop 0
	v_cndmask_b32_e32 v93, v77, v93, vcc
	v_fmamk_f32 v172, v172, 0x3fb8aa3b, v200
	v_cmp_le_i32_e32 vcc, 34, v198
	v_fmamk_f32 v94, v94, 0x3e38aa3b, v172
	s_nop 0
	v_cndmask_b32_e32 v94, v77, v94, vcc
	v_fmamk_f32 v173, v173, 0x3fb8aa3b, v200
	v_cmp_le_i32_e32 vcc, 35, v198
	v_fmamk_f32 v95, v95, 0x3e38aa3b, v173
	s_nop 0
	v_cndmask_b32_e32 v95, v77, v95, vcc
	v_fmamk_f32 v202, v202, 0x3fb8aa3b, v200
	v_cmp_le_i32_e32 vcc, 48, v198
	v_fmamk_f32 v96, v96, 0x3e38aa3b, v202
	s_nop 0
	v_cndmask_b32_e32 v96, v77, v96, vcc
	v_fmamk_f32 v203, v203, 0x3fb8aa3b, v200
	v_cmp_le_i32_e32 vcc, 49, v198
	v_fmamk_f32 v97, v97, 0x3e38aa3b, v203
	s_nop 0
	v_cndmask_b32_e32 v97, v77, v97, vcc
	v_fmamk_f32 v228, v228, 0x3fb8aa3b, v200
	v_cmp_le_i32_e32 vcc, 50, v198
	v_fmamk_f32 v98, v98, 0x3e38aa3b, v228
	s_nop 0
	v_cndmask_b32_e32 v98, v77, v98, vcc
	v_fmamk_f32 v229, v229, 0x3fb8aa3b, v200
	v_cmp_le_i32_e32 vcc, 51, v198
	v_fmamk_f32 v99, v99, 0x3e38aa3b, v229
	s_nop 0
	v_cndmask_b32_e32 v99, v77, v99, vcc
	s_branch .Lbm3_Ag3_max
